# G1: SEC2 LDS-transposed stores + SEC4 conditional RoPE-table loads issued together with one wait per group
# speedup vs baseline: 1.0050x; 1.0050x over previous
.LBB0_112:
	s_and_b64 vcc, exec, s[0:1]
	s_cbranch_vccz .LBB0_147
	s_lshl_b32 s0, s48, 8
	v_add_u32_e32 v190, s0, v241
	v_ashrrev_i32_e32 v191, 31, v190
	v_lshl_add_u64 v[152:153], v[190:191], 2, s[70:71]
	global_load_dword v188, v[152:153], off
	s_movk_i32 s0, 0x7cf
	v_and_or_b32 v2, v190, s0, 16
	v_cmp_gt_i32_e32 vcc, s20, v190
	v_mov_b32_e32 v198, 0
	v_mov_b32_e32 v132, 1.0
	v_cndmask_b32_e32 v2, v181, v2, vcc
	v_lshlrev_b32_e32 v2, 6, v2
	v_lshl_add_u64 v[136:137], s[84:85], 0, v[2:3]
	v_mov_b32_e32 v140, 1.0
	v_mov_b32_e32 v210, 0
	v_mov_b32_e32 v142, 1.0
	v_mov_b32_e32 v206, 0
	s_and_saveexec_b64 s[0:1], s[38:39]
	s_cbranch_execz .LBB0_115
	v_lshlrev_b32_e32 v2, 2, v170
	v_lshl_add_u64 v[134:135], v[136:137], 0, v[2:3]
	global_load_dwordx4 v[140:143], v[134:135], off
.LBB0_115:
	s_or_b64 exec, exec, s[0:1]
	v_mov_b32_e32 v134, 1.0
	v_mov_b32_e32 v214, 0
	s_and_saveexec_b64 s[0:1], s[38:39]
	s_cbranch_execz .LBB0_117
	v_lshlrev_b32_e32 v2, 2, v170
	v_lshl_add_u64 v[132:133], v[136:137], 0, v[2:3]
	global_load_dwordx4 v[132:135], v[132:133], off offset:16
.LBB0_117:
	s_or_b64 exec, exec, s[0:1]
	global_load_dword v196, v[152:153], off offset:64
	s_movk_i32 s0, 0x7df
	v_or_b32_e32 v192, 16, v190
	v_bitop3_b32 v2, v190, s0, 16 bitop3:0xc8
	v_add_u32_e32 v2, 16, v2
	v_cmp_gt_i32_e32 vcc, s20, v192
	v_mov_b32_e32 v204, 0
	v_mov_b32_e32 v136, 1.0
	v_cndmask_b32_e32 v2, v181, v2, vcc
	v_lshlrev_b32_e32 v2, 6, v2
	v_lshl_add_u64 v[144:145], s[84:85], 0, v[2:3]
	v_mov_b32_e32 v148, 1.0
	v_mov_b32_e32 v218, 0
	v_mov_b32_e32 v150, 1.0
	v_mov_b32_e32 v216, 0
	s_and_saveexec_b64 s[0:1], s[38:39]
	s_cbranch_execz .LBB0_119
	v_lshlrev_b32_e32 v2, 2, v170
	v_lshl_add_u64 v[138:139], v[144:145], 0, v[2:3]
	global_load_dwordx4 v[148:151], v[138:139], off
.LBB0_119:
	s_or_b64 exec, exec, s[0:1]
	v_mov_b32_e32 v138, 1.0
	v_mov_b32_e32 v222, 0
	s_and_saveexec_b64 s[0:1], s[38:39]
	s_cbranch_execz .LBB0_121
	v_lshlrev_b32_e32 v2, 2, v170
	v_lshl_add_u64 v[136:137], v[144:145], 0, v[2:3]
	global_load_dwordx4 v[136:139], v[136:137], off offset:16
.LBB0_121:
	s_or_b64 exec, exec, s[0:1]
	global_load_dword v202, v[152:153], off offset:128
	v_or_b32_e32 v194, 32, v190
	s_movk_i32 s0, 0x7ef
	v_and_or_b32 v2, v194, s0, 16
	v_cmp_gt_i32_e32 vcc, s20, v194
	v_mov_b32_e32 v212, 0
	v_mov_b32_e32 v144, 1.0
	v_cndmask_b32_e32 v2, v181, v2, vcc
	v_lshlrev_b32_e32 v2, 6, v2
	v_lshl_add_u64 v[154:155], s[84:85], 0, v[2:3]
	v_mov_b32_e32 v156, 1.0
	v_mov_b32_e32 v226, 0
	v_mov_b32_e32 v158, 1.0
	v_mov_b32_e32 v224, 0
	s_and_saveexec_b64 s[0:1], s[38:39]
	s_cbranch_execz .LBB0_123
	v_lshlrev_b32_e32 v2, 2, v170
	v_lshl_add_u64 v[146:147], v[154:155], 0, v[2:3]
	global_load_dwordx4 v[156:159], v[146:147], off
.LBB0_123:
	s_or_b64 exec, exec, s[0:1]
	v_mov_b32_e32 v146, 1.0
	v_mov_b32_e32 v228, 0
	s_and_saveexec_b64 s[0:1], s[38:39]
	s_cbranch_execz .LBB0_125
	v_lshlrev_b32_e32 v2, 2, v170
	v_lshl_add_u64 v[144:145], v[154:155], 0, v[2:3]
	global_load_dwordx4 v[144:147], v[144:145], off offset:16
.LBB0_125:
	s_or_b64 exec, exec, s[0:1]
	global_load_dword v208, v[152:153], off offset:192
	s_movk_i32 s0, 0x7ff
	v_or_b32_e32 v200, 48, v190
	v_bitop3_b32 v2, v190, s0, 48 bitop3:0xc8
	v_add_u32_e32 v2, 16, v2
	v_cmp_gt_i32_e32 vcc, s20, v200
	v_mov_b32_e32 v220, 0
	v_mov_b32_e32 v152, 1.0
	v_cndmask_b32_e32 v2, v181, v2, vcc
	v_lshlrev_b32_e32 v2, 6, v2
	v_lshl_add_u64 v[234:235], s[84:85], 0, v[2:3]
	v_mov_b32_e32 v160, 1.0
	v_mov_b32_e32 v232, 0
	v_mov_b32_e32 v162, 1.0
	v_mov_b32_e32 v230, 0
	s_and_saveexec_b64 s[0:1], s[38:39]
	s_cbranch_execz .LBB0_127
	v_lshlrev_b32_e32 v2, 2, v170
	v_lshl_add_u64 v[154:155], v[234:235], 0, v[2:3]
	global_load_dwordx4 v[160:163], v[154:155], off
.LBB0_127:
	s_or_b64 exec, exec, s[0:1]
	v_mov_b32_e32 v154, 1.0
	v_mov_b32_e32 v2, 0
	s_and_saveexec_b64 s[0:1], s[38:39]
	s_cbranch_execz .LBB0_129
	v_lshlrev_b32_e32 v2, 2, v170
	v_lshl_add_u64 v[152:153], v[234:235], 0, v[2:3]
	global_load_dwordx4 v[152:155], v[152:153], off offset:16
.LBB0_129:
	s_or_b64 exec, exec, s[0:1]
	s_waitcnt vmcnt(0)
	s_and_saveexec_b64 s[0:1], s[38:39]
	v_mov_b32_e32 v210, v141
	v_mov_b32_e32 v206, v143
	v_mov_b32_e32 v198, v133
	v_mov_b32_e32 v214, v135
	v_mov_b32_e32 v218, v149
	v_mov_b32_e32 v216, v151
	v_mov_b32_e32 v204, v137
	v_mov_b32_e32 v222, v139
	v_mov_b32_e32 v226, v157
	v_mov_b32_e32 v224, v159
	v_mov_b32_e32 v212, v145
	v_mov_b32_e32 v228, v147
	v_mov_b32_e32 v232, v161
	v_mov_b32_e32 v230, v163
	v_mov_b32_e32 v220, v153
	v_mov_b32_e32 v2, v155
	s_or_b64 exec, exec, s[0:1]
	v_pk_mul_f32 v[168:169], v[128:129], v[188:189] op_sel_hi:[1,0]
	v_pk_mul_f32 v[236:237], v[130:131], v[188:189] op_sel_hi:[1,0]
	v_pk_mul_f32 v[210:211], v[168:169], v[210:211] op_sel:[1,0] op_sel_hi:[0,0]
	v_pk_fma_f32 v[238:239], v[168:169], v[140:141], v[210:211] op_sel_hi:[1,0,1] neg_lo:[0,0,1] neg_hi:[0,0,1]
	v_pk_fma_f32 v[140:141], v[168:169], v[140:141], v[210:211] op_sel_hi:[1,0,1]
	v_pk_mul_f32 v[168:169], v[236:237], v[206:207] op_sel:[1,0] op_sel_hi:[0,0]
	v_pk_fma_f32 v[206:207], v[236:237], v[142:143], v[168:169] op_sel_hi:[1,0,1] neg_lo:[0,0,1] neg_hi:[0,0,1]
	v_pk_fma_f32 v[142:143], v[236:237], v[142:143], v[168:169] op_sel_hi:[1,0,1]
	v_pk_mul_f32 v[168:169], v[126:127], v[188:189] op_sel_hi:[1,0]
	v_pk_mul_f32 v[188:189], v[124:125], v[188:189] op_sel_hi:[1,0]
	v_mov_b32_e32 v207, v143
	s_mov_b32 s4, 0x3e000000
	v_pk_mul_f32 v[198:199], v[188:189], v[198:199] op_sel:[1,0] op_sel_hi:[0,0]
	v_or_b32_e32 v234, s74, v178
	v_pk_mul_f32 v[142:143], v[206:207], s[4:5] op_sel_hi:[1,0]
	v_pk_fma_f32 v[206:207], v[188:189], v[132:133], v[198:199] op_sel_hi:[1,0,1] neg_lo:[0,0,1] neg_hi:[0,0,1]
	v_pk_fma_f32 v[132:133], v[188:189], v[132:133], v[198:199] op_sel_hi:[1,0,1]
	v_pk_mul_f32 v[188:189], v[168:169], v[214:215] op_sel:[1,0] op_sel_hi:[0,0]
	v_ashrrev_i32_e32 v235, 31, v234
	v_pk_fma_f32 v[198:199], v[168:169], v[134:135], v[188:189] op_sel_hi:[1,0,1] neg_lo:[0,0,1] neg_hi:[0,0,1]
	v_pk_fma_f32 v[134:135], v[168:169], v[134:135], v[188:189] op_sel_hi:[1,0,1]
	v_mov_b32_e32 v207, v133
	v_lshlrev_b64 v[132:133], 10, v[190:191]
	v_mov_b32_e32 v239, v141
	v_mov_b32_e32 v199, v135
	v_lshl_add_u64 v[132:133], s[94:95], 0, v[132:133]
	v_lshlrev_b64 v[188:189], 1, v[234:235]
	v_pk_mul_f32 v[140:141], v[238:239], s[4:5] op_sel_hi:[1,0]
	v_pk_mul_f32 v[168:169], v[198:199], s[4:5] op_sel_hi:[1,0]
	v_lshl_add_u64 v[198:199], v[132:133], 0, v[188:189]
	s_mov_b32 s0, 0x847e000
	v_pk_mul_f32 v[134:135], v[206:207], s[4:5] op_sel_hi:[1,0]
	v_cvt_pk_bf16_f32 v132, v140, v141
	v_add_co_u32_e32 v140, vcc, s0, v198
	v_cvt_pk_bf16_f32 v133, v142, v143
	v_cvt_pk_bf16_f32 v134, v134, v135
	v_cvt_pk_bf16_f32 v135, v168, v169
	v_addc_co_u32_e32 v141, vcc, 0, v199, vcc
	global_store_dwordx4 v[140:141], v[132:135], off offset:2048
	v_ashrrev_i32_e32 v193, 31, v192
	v_ashrrev_i32_e32 v195, 31, v194
	v_pk_mul_f32 v[134:135], v[120:121], v[196:197] op_sel_hi:[1,0]
	v_pk_mul_f32 v[132:133], v[122:123], v[196:197] op_sel_hi:[1,0]
	v_pk_mul_f32 v[140:141], v[134:135], v[218:219] op_sel:[1,0] op_sel_hi:[0,0]
	v_pk_fma_f32 v[142:143], v[134:135], v[148:149], v[140:141] op_sel_hi:[1,0,1] neg_lo:[0,0,1] neg_hi:[0,0,1]
	v_pk_fma_f32 v[134:135], v[134:135], v[148:149], v[140:141] op_sel_hi:[1,0,1]
	v_pk_mul_f32 v[140:141], v[132:133], v[216:217] op_sel:[1,0] op_sel_hi:[0,0]
	v_pk_fma_f32 v[148:149], v[132:133], v[150:151], v[140:141] op_sel_hi:[1,0,1] neg_lo:[0,0,1] neg_hi:[0,0,1]
	v_pk_fma_f32 v[132:133], v[132:133], v[150:151], v[140:141] op_sel_hi:[1,0,1]
	v_mov_b32_e32 v143, v135
	v_mov_b32_e32 v149, v133
	v_pk_mul_f32 v[132:133], v[142:143], s[4:5] op_sel_hi:[1,0]
	v_pk_mul_f32 v[142:143], v[116:117], v[196:197] op_sel_hi:[1,0]
	v_pk_mul_f32 v[140:141], v[148:149], s[4:5] op_sel_hi:[1,0]
	v_pk_mul_f32 v[148:149], v[142:143], v[204:205] op_sel:[1,0] op_sel_hi:[0,0]
	v_pk_mul_f32 v[134:135], v[118:119], v[196:197] op_sel_hi:[1,0]
	v_pk_fma_f32 v[150:151], v[142:143], v[136:137], v[148:149] op_sel_hi:[1,0,1] neg_lo:[0,0,1] neg_hi:[0,0,1]
	v_pk_fma_f32 v[136:137], v[142:143], v[136:137], v[148:149] op_sel_hi:[1,0,1]
	v_pk_mul_f32 v[142:143], v[134:135], v[222:223] op_sel:[1,0] op_sel_hi:[0,0]
	v_mov_b32_e32 v151, v137
	v_lshlrev_b64 v[136:137], 10, v[192:193]
	v_pk_fma_f32 v[148:149], v[134:135], v[138:139], v[142:143] op_sel_hi:[1,0,1] neg_lo:[0,0,1] neg_hi:[0,0,1]
	v_pk_fma_f32 v[134:135], v[134:135], v[138:139], v[142:143] op_sel_hi:[1,0,1]
	v_lshl_add_u64 v[136:137], s[94:95], 0, v[136:137]
	v_mov_b32_e32 v149, v135
	v_lshl_add_u64 v[136:137], v[136:137], 0, v[188:189]
	v_pk_mul_f32 v[138:139], v[148:149], s[4:5] op_sel_hi:[1,0]
	v_pk_mul_f32 v[134:135], v[150:151], s[4:5] op_sel_hi:[1,0]
	v_add_co_u32_e32 v136, vcc, s0, v136
	v_cvt_pk_bf16_f32 v132, v132, v133
	v_cvt_pk_bf16_f32 v133, v140, v141
	v_cvt_pk_bf16_f32 v134, v134, v135
	v_cvt_pk_bf16_f32 v135, v138, v139
	v_addc_co_u32_e32 v137, vcc, 0, v137, vcc
	global_store_dwordx4 v[136:137], v[132:135], off offset:2048
	v_ashrrev_i32_e32 v201, 31, v200
	s_cmp_eq_u32 s48, 64
	v_pk_mul_f32 v[134:135], v[112:113], v[202:203] op_sel_hi:[1,0]
	v_pk_mul_f32 v[132:133], v[114:115], v[202:203] op_sel_hi:[1,0]
	v_pk_mul_f32 v[136:137], v[134:135], v[226:227] op_sel:[1,0] op_sel_hi:[0,0]
	v_pk_fma_f32 v[138:139], v[134:135], v[156:157], v[136:137] op_sel_hi:[1,0,1] neg_lo:[0,0,1] neg_hi:[0,0,1]
	v_pk_fma_f32 v[134:135], v[134:135], v[156:157], v[136:137] op_sel_hi:[1,0,1]
	v_pk_mul_f32 v[136:137], v[132:133], v[224:225] op_sel:[1,0] op_sel_hi:[0,0]
	v_pk_fma_f32 v[140:141], v[132:133], v[158:159], v[136:137] op_sel_hi:[1,0,1] neg_lo:[0,0,1] neg_hi:[0,0,1]
	v_pk_fma_f32 v[132:133], v[132:133], v[158:159], v[136:137] op_sel_hi:[1,0,1]
	v_mov_b32_e32 v139, v135
	v_mov_b32_e32 v141, v133
	v_pk_mul_f32 v[132:133], v[138:139], s[4:5] op_sel_hi:[1,0]
	v_pk_mul_f32 v[138:139], v[108:109], v[202:203] op_sel_hi:[1,0]
	v_pk_mul_f32 v[136:137], v[140:141], s[4:5] op_sel_hi:[1,0]
	v_pk_mul_f32 v[140:141], v[138:139], v[212:213] op_sel:[1,0] op_sel_hi:[0,0]
	v_pk_mul_f32 v[134:135], v[110:111], v[202:203] op_sel_hi:[1,0]
	v_pk_fma_f32 v[142:143], v[138:139], v[144:145], v[140:141] op_sel_hi:[1,0,1] neg_lo:[0,0,1] neg_hi:[0,0,1]
	v_pk_fma_f32 v[138:139], v[138:139], v[144:145], v[140:141] op_sel_hi:[1,0,1]
	v_pk_mul_f32 v[140:141], v[134:135], v[228:229] op_sel:[1,0] op_sel_hi:[0,0]
	v_mov_b32_e32 v143, v139
	v_lshlrev_b64 v[138:139], 10, v[194:195]
	v_pk_fma_f32 v[144:145], v[134:135], v[146:147], v[140:141] op_sel_hi:[1,0,1] neg_lo:[0,0,1] neg_hi:[0,0,1]
	v_pk_fma_f32 v[134:135], v[134:135], v[146:147], v[140:141] op_sel_hi:[1,0,1]
	v_lshl_add_u64 v[138:139], s[94:95], 0, v[138:139]
	v_mov_b32_e32 v145, v135
	v_lshl_add_u64 v[138:139], v[138:139], 0, v[188:189]
	v_pk_mul_f32 v[140:141], v[144:145], s[4:5] op_sel_hi:[1,0]
	v_pk_mul_f32 v[134:135], v[142:143], s[4:5] op_sel_hi:[1,0]
	v_cvt_pk_bf16_f32 v132, v132, v133
	v_cvt_pk_bf16_f32 v133, v136, v137
	v_add_co_u32_e32 v136, vcc, s0, v138
	v_cvt_pk_bf16_f32 v134, v134, v135
	v_cvt_pk_bf16_f32 v135, v140, v141
	v_addc_co_u32_e32 v137, vcc, 0, v139, vcc
	global_store_dwordx4 v[136:137], v[132:135], off offset:2048
	s_nop 1
	v_pk_mul_f32 v[134:135], v[104:105], v[208:209] op_sel_hi:[1,0]
	v_pk_mul_f32 v[132:133], v[106:107], v[208:209] op_sel_hi:[1,0]
	v_pk_mul_f32 v[136:137], v[134:135], v[232:233] op_sel:[1,0] op_sel_hi:[0,0]
	v_pk_fma_f32 v[138:139], v[134:135], v[160:161], v[136:137] op_sel_hi:[1,0,1] neg_lo:[0,0,1] neg_hi:[0,0,1]
	v_pk_fma_f32 v[134:135], v[134:135], v[160:161], v[136:137] op_sel_hi:[1,0,1]
	v_pk_mul_f32 v[136:137], v[132:133], v[230:231] op_sel:[1,0] op_sel_hi:[0,0]
	v_pk_fma_f32 v[140:141], v[132:133], v[162:163], v[136:137] op_sel_hi:[1,0,1] neg_lo:[0,0,1] neg_hi:[0,0,1]
	v_pk_fma_f32 v[132:133], v[132:133], v[162:163], v[136:137] op_sel_hi:[1,0,1]
	v_mov_b32_e32 v139, v135
	v_mov_b32_e32 v141, v133
	v_pk_mul_f32 v[132:133], v[138:139], s[4:5] op_sel_hi:[1,0]
	v_pk_mul_f32 v[138:139], v[100:101], v[208:209] op_sel_hi:[1,0]
	v_pk_mul_f32 v[136:137], v[140:141], s[4:5] op_sel_hi:[1,0]
	v_pk_mul_f32 v[140:141], v[138:139], v[220:221] op_sel:[1,0] op_sel_hi:[0,0]
	v_pk_mul_f32 v[134:135], v[102:103], v[208:209] op_sel_hi:[1,0]
	v_pk_fma_f32 v[142:143], v[138:139], v[152:153], v[140:141] op_sel_hi:[1,0,1] neg_lo:[0,0,1] neg_hi:[0,0,1]
	v_pk_fma_f32 v[138:139], v[138:139], v[152:153], v[140:141] op_sel_hi:[1,0,1]
	v_pk_mul_f32 v[140:141], v[134:135], v[2:3] op_sel:[1,0] op_sel_hi:[0,0]
	v_mov_b32_e32 v143, v139
	v_lshlrev_b64 v[138:139], 10, v[200:201]
	v_pk_fma_f32 v[144:145], v[134:135], v[154:155], v[140:141] op_sel_hi:[1,0,1] neg_lo:[0,0,1] neg_hi:[0,0,1]
	v_pk_fma_f32 v[134:135], v[134:135], v[154:155], v[140:141] op_sel_hi:[1,0,1]
	v_lshl_add_u64 v[138:139], s[94:95], 0, v[138:139]
	v_mov_b32_e32 v145, v135
	v_lshl_add_u64 v[138:139], v[138:139], 0, v[188:189]
	v_pk_mul_f32 v[140:141], v[144:145], s[4:5] op_sel_hi:[1,0]
	v_pk_mul_f32 v[134:135], v[142:143], s[4:5] op_sel_hi:[1,0]
	v_cvt_pk_bf16_f32 v132, v132, v133
	v_cvt_pk_bf16_f32 v133, v136, v137
	v_add_co_u32_e32 v136, vcc, 0x847e000, v138
	v_cvt_pk_bf16_f32 v134, v134, v135
	v_cvt_pk_bf16_f32 v135, v140, v141
	v_addc_co_u32_e32 v137, vcc, 0, v139, vcc
	global_store_dwordx4 v[136:137], v[132:135], off offset:2048
	s_cbranch_scc1 .LBB0_147
	v_add_u32_e32 v190, 0x80, v190
	v_ashrrev_i32_e32 v191, 31, v190
	v_lshl_add_u64 v[152:153], v[190:191], 2, s[70:71]
	global_load_dword v194, v[152:153], off
	s_movk_i32 s0, 0x7cf
	v_and_or_b32 v2, v190, s0, 16
	v_cmp_gt_i32_e32 vcc, s20, v190
	v_mov_b32_e32 v200, 0
	v_mov_b32_e32 v132, 1.0
	v_cndmask_b32_e32 v2, v181, v2, vcc
	v_lshlrev_b32_e32 v2, 6, v2
	v_lshl_add_u64 v[136:137], s[84:85], 0, v[2:3]
	v_mov_b32_e32 v140, 1.0
	v_mov_b32_e32 v210, 0
	v_mov_b32_e32 v142, 1.0
	v_mov_b32_e32 v208, 0
	s_and_saveexec_b64 s[0:1], s[38:39]
	s_cbranch_execz .LBB0_132
	v_lshlrev_b32_e32 v2, 2, v170
	v_lshl_add_u64 v[134:135], v[136:137], 0, v[2:3]
	global_load_dwordx4 v[140:143], v[134:135], off
.LBB0_132:
	s_or_b64 exec, exec, s[0:1]
	v_mov_b32_e32 v134, 1.0
	v_mov_b32_e32 v216, 0
	s_and_saveexec_b64 s[0:1], s[38:39]
	s_cbranch_execz .LBB0_134
	v_lshlrev_b32_e32 v2, 2, v170
	v_lshl_add_u64 v[132:133], v[136:137], 0, v[2:3]
	global_load_dwordx4 v[132:135], v[132:133], off offset:16
.LBB0_134:
	s_or_b64 exec, exec, s[0:1]
	global_load_dword v198, v[152:153], off offset:64
	s_movk_i32 s0, 0x7df
	v_or_b32_e32 v192, 16, v190
	v_bitop3_b32 v2, v190, s0, 16 bitop3:0xc8
	v_add_u32_e32 v2, 16, v2
	v_cmp_gt_i32_e32 vcc, s20, v192
	v_mov_b32_e32 v206, 0
	v_mov_b32_e32 v136, 1.0
	v_cndmask_b32_e32 v2, v181, v2, vcc
	v_lshlrev_b32_e32 v2, 6, v2
	v_lshl_add_u64 v[144:145], s[84:85], 0, v[2:3]
	v_mov_b32_e32 v148, 1.0
	v_mov_b32_e32 v220, 0
	v_mov_b32_e32 v150, 1.0
	v_mov_b32_e32 v218, 0
	s_and_saveexec_b64 s[0:1], s[38:39]
	s_cbranch_execz .LBB0_136
	v_lshlrev_b32_e32 v2, 2, v170
	v_lshl_add_u64 v[138:139], v[144:145], 0, v[2:3]
	global_load_dwordx4 v[148:151], v[138:139], off
.LBB0_136:
	s_or_b64 exec, exec, s[0:1]
	v_mov_b32_e32 v138, 1.0
	v_mov_b32_e32 v224, 0
	s_and_saveexec_b64 s[0:1], s[38:39]
	s_cbranch_execz .LBB0_138
	v_lshlrev_b32_e32 v2, 2, v170
	v_lshl_add_u64 v[136:137], v[144:145], 0, v[2:3]
	global_load_dwordx4 v[136:139], v[136:137], off offset:16
.LBB0_138:
	s_or_b64 exec, exec, s[0:1]
	global_load_dword v204, v[152:153], off offset:128
	v_or_b32_e32 v196, 32, v190
	s_movk_i32 s0, 0x7ef
	v_and_or_b32 v2, v196, s0, 16
	v_cmp_gt_i32_e32 vcc, s20, v196
	v_mov_b32_e32 v214, 0
	v_mov_b32_e32 v144, 1.0
	v_cndmask_b32_e32 v2, v181, v2, vcc
	v_lshlrev_b32_e32 v2, 6, v2
	v_lshl_add_u64 v[154:155], s[84:85], 0, v[2:3]
	v_mov_b32_e32 v156, 1.0
	v_mov_b32_e32 v228, 0
	v_mov_b32_e32 v158, 1.0
	v_mov_b32_e32 v226, 0
	s_and_saveexec_b64 s[0:1], s[38:39]
	s_cbranch_execz .LBB0_140
	v_lshlrev_b32_e32 v2, 2, v170
	v_lshl_add_u64 v[146:147], v[154:155], 0, v[2:3]
	global_load_dwordx4 v[156:159], v[146:147], off
.LBB0_140:
	s_or_b64 exec, exec, s[0:1]
	v_mov_b32_e32 v146, 1.0
	v_mov_b32_e32 v230, 0
	s_and_saveexec_b64 s[0:1], s[38:39]
	s_cbranch_execz .LBB0_142
	v_lshlrev_b32_e32 v2, 2, v170
	v_lshl_add_u64 v[144:145], v[154:155], 0, v[2:3]
	global_load_dwordx4 v[144:147], v[144:145], off offset:16
.LBB0_142:
	s_or_b64 exec, exec, s[0:1]
	global_load_dword v212, v[152:153], off offset:192
	s_movk_i32 s0, 0x7ff
	v_or_b32_e32 v202, 48, v190
	v_bitop3_b32 v2, v190, s0, 48 bitop3:0xc8
	v_add_u32_e32 v2, 16, v2
	v_cmp_gt_i32_e32 vcc, s20, v202
	v_mov_b32_e32 v222, 0
	v_mov_b32_e32 v152, 1.0
	v_cndmask_b32_e32 v2, v181, v2, vcc
	v_lshlrev_b32_e32 v2, 6, v2
	v_lshl_add_u64 v[236:237], s[84:85], 0, v[2:3]
	v_mov_b32_e32 v160, 1.0
	v_mov_b32_e32 v234, 0
	v_mov_b32_e32 v162, 1.0
	v_mov_b32_e32 v232, 0
	s_and_saveexec_b64 s[0:1], s[38:39]
	s_cbranch_execz .LBB0_144
	v_lshlrev_b32_e32 v2, 2, v170
	v_lshl_add_u64 v[154:155], v[236:237], 0, v[2:3]
	global_load_dwordx4 v[160:163], v[154:155], off
.LBB0_144:
	s_or_b64 exec, exec, s[0:1]
	v_mov_b32_e32 v154, 1.0
	v_mov_b32_e32 v2, 0
	s_and_saveexec_b64 s[0:1], s[38:39]
	s_cbranch_execz .LBB0_146
	v_lshlrev_b32_e32 v2, 2, v170
	v_lshl_add_u64 v[152:153], v[236:237], 0, v[2:3]
	global_load_dwordx4 v[152:155], v[152:153], off offset:16
.LBB0_146:
	s_or_b64 exec, exec, s[0:1]
	s_waitcnt vmcnt(0)
	s_and_saveexec_b64 s[0:1], s[38:39]
	v_mov_b32_e32 v210, v141
	v_mov_b32_e32 v208, v143
	v_mov_b32_e32 v200, v133
	v_mov_b32_e32 v216, v135
	v_mov_b32_e32 v220, v149
	v_mov_b32_e32 v218, v151
	v_mov_b32_e32 v206, v137
	v_mov_b32_e32 v224, v139
	v_mov_b32_e32 v228, v157
	v_mov_b32_e32 v226, v159
	v_mov_b32_e32 v214, v145
	v_mov_b32_e32 v230, v147
	v_mov_b32_e32 v234, v161
	v_mov_b32_e32 v232, v163
	v_mov_b32_e32 v222, v153
	v_mov_b32_e32 v2, v155
	s_or_b64 exec, exec, s[0:1]
	v_pk_mul_f32 v[168:169], v[98:99], v[194:195] op_sel_hi:[1,0]
	v_pk_mul_f32 v[236:237], v[96:97], v[194:195] op_sel_hi:[1,0]
	v_pk_mul_f32 v[208:209], v[168:169], v[208:209] op_sel:[1,0] op_sel_hi:[0,0]
	v_pk_mul_f32 v[210:211], v[236:237], v[210:211] op_sel:[1,0] op_sel_hi:[0,0]
	v_pk_fma_f32 v[238:239], v[236:237], v[140:141], v[210:211] op_sel_hi:[1,0,1] neg_lo:[0,0,1] neg_hi:[0,0,1]
	v_pk_fma_f32 v[140:141], v[236:237], v[140:141], v[210:211] op_sel_hi:[1,0,1]
	v_pk_fma_f32 v[210:211], v[168:169], v[142:143], v[208:209] op_sel_hi:[1,0,1] neg_lo:[0,0,1] neg_hi:[0,0,1]
	v_pk_fma_f32 v[142:143], v[168:169], v[142:143], v[208:209] op_sel_hi:[1,0,1]
	v_pk_mul_f32 v[168:169], v[94:95], v[194:195] op_sel_hi:[1,0]
	v_pk_mul_f32 v[194:195], v[92:93], v[194:195] op_sel_hi:[1,0]
	v_mov_b32_e32 v239, v141
	v_pk_mul_f32 v[200:201], v[194:195], v[200:201] op_sel:[1,0] op_sel_hi:[0,0]
	v_pk_fma_f32 v[208:209], v[194:195], v[132:133], v[200:201] op_sel_hi:[1,0,1] neg_lo:[0,0,1] neg_hi:[0,0,1]
	v_pk_fma_f32 v[132:133], v[194:195], v[132:133], v[200:201] op_sel_hi:[1,0,1]
	v_pk_mul_f32 v[194:195], v[168:169], v[216:217] op_sel:[1,0] op_sel_hi:[0,0]
	v_mov_b32_e32 v209, v133
	v_lshlrev_b64 v[132:133], 10, v[190:191]
	v_pk_fma_f32 v[200:201], v[168:169], v[134:135], v[194:195] op_sel_hi:[1,0,1] neg_lo:[0,0,1] neg_hi:[0,0,1]
	v_pk_fma_f32 v[134:135], v[168:169], v[134:135], v[194:195] op_sel_hi:[1,0,1]
	v_lshl_add_u64 v[132:133], s[94:95], 0, v[132:133]
	v_mov_b32_e32 v211, v143
	v_pk_mul_f32 v[140:141], v[238:239], s[4:5] op_sel_hi:[1,0]
	v_mov_b32_e32 v201, v135
	v_lshl_add_u64 v[190:191], v[132:133], 0, v[188:189]
	s_mov_b32 s0, 0x847e000
	v_pk_mul_f32 v[142:143], v[210:211], s[4:5] op_sel_hi:[1,0]
	v_pk_mul_f32 v[168:169], v[200:201], s[4:5] op_sel_hi:[1,0]
	v_pk_mul_f32 v[134:135], v[208:209], s[4:5] op_sel_hi:[1,0]
	v_cvt_pk_bf16_f32 v132, v140, v141
	v_add_co_u32_e32 v140, vcc, s0, v190
	v_cvt_pk_bf16_f32 v133, v142, v143
	v_cvt_pk_bf16_f32 v134, v134, v135
	v_cvt_pk_bf16_f32 v135, v168, v169
	v_addc_co_u32_e32 v141, vcc, 0, v191, vcc
	global_store_dwordx4 v[140:141], v[132:135], off offset:2048
	v_ashrrev_i32_e32 v193, 31, v192
	v_ashrrev_i32_e32 v197, 31, v196
	v_pk_mul_f32 v[134:135], v[88:89], v[198:199] op_sel_hi:[1,0]
	v_pk_mul_f32 v[132:133], v[90:91], v[198:199] op_sel_hi:[1,0]
	v_pk_mul_f32 v[140:141], v[134:135], v[220:221] op_sel:[1,0] op_sel_hi:[0,0]
	v_pk_fma_f32 v[142:143], v[134:135], v[148:149], v[140:141] op_sel_hi:[1,0,1] neg_lo:[0,0,1] neg_hi:[0,0,1]
	v_pk_fma_f32 v[134:135], v[134:135], v[148:149], v[140:141] op_sel_hi:[1,0,1]
	v_pk_mul_f32 v[140:141], v[132:133], v[218:219] op_sel:[1,0] op_sel_hi:[0,0]
	v_pk_fma_f32 v[148:149], v[132:133], v[150:151], v[140:141] op_sel_hi:[1,0,1] neg_lo:[0,0,1] neg_hi:[0,0,1]
	v_pk_fma_f32 v[132:133], v[132:133], v[150:151], v[140:141] op_sel_hi:[1,0,1]
	v_mov_b32_e32 v143, v135
	v_mov_b32_e32 v149, v133
	v_pk_mul_f32 v[132:133], v[142:143], s[4:5] op_sel_hi:[1,0]
	v_pk_mul_f32 v[142:143], v[84:85], v[198:199] op_sel_hi:[1,0]
	v_pk_mul_f32 v[140:141], v[148:149], s[4:5] op_sel_hi:[1,0]
	v_pk_mul_f32 v[148:149], v[142:143], v[206:207] op_sel:[1,0] op_sel_hi:[0,0]
	v_pk_mul_f32 v[134:135], v[86:87], v[198:199] op_sel_hi:[1,0]
	v_pk_fma_f32 v[150:151], v[142:143], v[136:137], v[148:149] op_sel_hi:[1,0,1] neg_lo:[0,0,1] neg_hi:[0,0,1]
	v_pk_fma_f32 v[136:137], v[142:143], v[136:137], v[148:149] op_sel_hi:[1,0,1]
	v_pk_mul_f32 v[142:143], v[134:135], v[224:225] op_sel:[1,0] op_sel_hi:[0,0]
	v_mov_b32_e32 v151, v137
	v_lshlrev_b64 v[136:137], 10, v[192:193]
	v_pk_fma_f32 v[148:149], v[134:135], v[138:139], v[142:143] op_sel_hi:[1,0,1] neg_lo:[0,0,1] neg_hi:[0,0,1]
	v_pk_fma_f32 v[134:135], v[134:135], v[138:139], v[142:143] op_sel_hi:[1,0,1]
	v_lshl_add_u64 v[136:137], s[94:95], 0, v[136:137]
	v_mov_b32_e32 v149, v135
	v_lshl_add_u64 v[136:137], v[136:137], 0, v[188:189]
	v_pk_mul_f32 v[138:139], v[148:149], s[4:5] op_sel_hi:[1,0]
	v_pk_mul_f32 v[134:135], v[150:151], s[4:5] op_sel_hi:[1,0]
	v_add_co_u32_e32 v136, vcc, s0, v136
	v_cvt_pk_bf16_f32 v132, v132, v133
	v_cvt_pk_bf16_f32 v133, v140, v141
	v_cvt_pk_bf16_f32 v134, v134, v135
	v_cvt_pk_bf16_f32 v135, v138, v139
	v_addc_co_u32_e32 v137, vcc, 0, v137, vcc
	global_store_dwordx4 v[136:137], v[132:135], off offset:2048
	v_ashrrev_i32_e32 v203, 31, v202
	s_nop 0
	v_pk_mul_f32 v[134:135], v[80:81], v[204:205] op_sel_hi:[1,0]
	v_pk_mul_f32 v[132:133], v[82:83], v[204:205] op_sel_hi:[1,0]
	v_pk_mul_f32 v[136:137], v[134:135], v[228:229] op_sel:[1,0] op_sel_hi:[0,0]
	v_pk_fma_f32 v[138:139], v[134:135], v[156:157], v[136:137] op_sel_hi:[1,0,1] neg_lo:[0,0,1] neg_hi:[0,0,1]
	v_pk_fma_f32 v[134:135], v[134:135], v[156:157], v[136:137] op_sel_hi:[1,0,1]
	v_pk_mul_f32 v[136:137], v[132:133], v[226:227] op_sel:[1,0] op_sel_hi:[0,0]
	v_pk_fma_f32 v[140:141], v[132:133], v[158:159], v[136:137] op_sel_hi:[1,0,1] neg_lo:[0,0,1] neg_hi:[0,0,1]
	v_pk_fma_f32 v[132:133], v[132:133], v[158:159], v[136:137] op_sel_hi:[1,0,1]
	v_mov_b32_e32 v139, v135
	v_mov_b32_e32 v141, v133
	v_pk_mul_f32 v[132:133], v[138:139], s[4:5] op_sel_hi:[1,0]
	v_pk_mul_f32 v[138:139], v[76:77], v[204:205] op_sel_hi:[1,0]
	v_pk_mul_f32 v[136:137], v[140:141], s[4:5] op_sel_hi:[1,0]
	v_pk_mul_f32 v[140:141], v[138:139], v[214:215] op_sel:[1,0] op_sel_hi:[0,0]
	v_pk_mul_f32 v[134:135], v[78:79], v[204:205] op_sel_hi:[1,0]
	v_pk_fma_f32 v[142:143], v[138:139], v[144:145], v[140:141] op_sel_hi:[1,0,1] neg_lo:[0,0,1] neg_hi:[0,0,1]
	v_pk_fma_f32 v[138:139], v[138:139], v[144:145], v[140:141] op_sel_hi:[1,0,1]
	v_pk_mul_f32 v[140:141], v[134:135], v[230:231] op_sel:[1,0] op_sel_hi:[0,0]
	v_mov_b32_e32 v143, v139
	v_lshlrev_b64 v[138:139], 10, v[196:197]
	v_pk_fma_f32 v[144:145], v[134:135], v[146:147], v[140:141] op_sel_hi:[1,0,1] neg_lo:[0,0,1] neg_hi:[0,0,1]
	v_pk_fma_f32 v[134:135], v[134:135], v[146:147], v[140:141] op_sel_hi:[1,0,1]
	v_lshl_add_u64 v[138:139], s[94:95], 0, v[138:139]
	v_mov_b32_e32 v145, v135
	v_lshl_add_u64 v[138:139], v[138:139], 0, v[188:189]
	v_pk_mul_f32 v[140:141], v[144:145], s[4:5] op_sel_hi:[1,0]
	v_pk_mul_f32 v[134:135], v[142:143], s[4:5] op_sel_hi:[1,0]
	v_cvt_pk_bf16_f32 v132, v132, v133
	v_cvt_pk_bf16_f32 v133, v136, v137
	v_add_co_u32_e32 v136, vcc, s0, v138
	v_cvt_pk_bf16_f32 v134, v134, v135
	v_cvt_pk_bf16_f32 v135, v140, v141
	v_addc_co_u32_e32 v137, vcc, 0, v139, vcc
	global_store_dwordx4 v[136:137], v[132:135], off offset:2048
	s_nop 1
	v_pk_mul_f32 v[134:135], v[72:73], v[212:213] op_sel_hi:[1,0]
	v_pk_mul_f32 v[132:133], v[74:75], v[212:213] op_sel_hi:[1,0]
	v_pk_mul_f32 v[136:137], v[134:135], v[234:235] op_sel:[1,0] op_sel_hi:[0,0]
	v_pk_fma_f32 v[138:139], v[134:135], v[160:161], v[136:137] op_sel_hi:[1,0,1] neg_lo:[0,0,1] neg_hi:[0,0,1]
	v_pk_fma_f32 v[134:135], v[134:135], v[160:161], v[136:137] op_sel_hi:[1,0,1]
	v_pk_mul_f32 v[136:137], v[132:133], v[232:233] op_sel:[1,0] op_sel_hi:[0,0]
	v_pk_fma_f32 v[140:141], v[132:133], v[162:163], v[136:137] op_sel_hi:[1,0,1] neg_lo:[0,0,1] neg_hi:[0,0,1]
	v_pk_fma_f32 v[132:133], v[132:133], v[162:163], v[136:137] op_sel_hi:[1,0,1]
	v_mov_b32_e32 v139, v135
	v_mov_b32_e32 v141, v133
	v_pk_mul_f32 v[132:133], v[138:139], s[4:5] op_sel_hi:[1,0]
	v_pk_mul_f32 v[138:139], v[68:69], v[212:213] op_sel_hi:[1,0]
	v_pk_mul_f32 v[136:137], v[140:141], s[4:5] op_sel_hi:[1,0]
	v_pk_mul_f32 v[140:141], v[138:139], v[222:223] op_sel:[1,0] op_sel_hi:[0,0]
	v_pk_mul_f32 v[134:135], v[70:71], v[212:213] op_sel_hi:[1,0]
	v_pk_fma_f32 v[142:143], v[138:139], v[152:153], v[140:141] op_sel_hi:[1,0,1] neg_lo:[0,0,1] neg_hi:[0,0,1]
	v_pk_fma_f32 v[138:139], v[138:139], v[152:153], v[140:141] op_sel_hi:[1,0,1]
	v_pk_mul_f32 v[140:141], v[134:135], v[2:3] op_sel:[1,0] op_sel_hi:[0,0]
	v_mov_b32_e32 v143, v139
	v_lshlrev_b64 v[138:139], 10, v[202:203]
	v_pk_fma_f32 v[144:145], v[134:135], v[154:155], v[140:141] op_sel_hi:[1,0,1] neg_lo:[0,0,1] neg_hi:[0,0,1]
	v_pk_fma_f32 v[134:135], v[134:135], v[154:155], v[140:141] op_sel_hi:[1,0,1]
	v_lshl_add_u64 v[138:139], s[94:95], 0, v[138:139]
	v_mov_b32_e32 v145, v135
	v_lshl_add_u64 v[138:139], v[138:139], 0, v[188:189]
	v_pk_mul_f32 v[140:141], v[144:145], s[4:5] op_sel_hi:[1,0]
	v_pk_mul_f32 v[134:135], v[142:143], s[4:5] op_sel_hi:[1,0]
	v_cvt_pk_bf16_f32 v132, v132, v133
	v_cvt_pk_bf16_f32 v133, v136, v137
	v_add_co_u32_e32 v136, vcc, 0x847e000, v138
	v_cvt_pk_bf16_f32 v134, v134, v135
	v_cvt_pk_bf16_f32 v135, v140, v141
	v_addc_co_u32_e32 v137, vcc, 0, v139, vcc
	global_store_dwordx4 v[136:137], v[132:135], off offset:2048

.LBB0_190:
	s_andn2_b64 vcc, exec, s[4:5]
	s_cbranch_vccnz .LBB0_225
	s_lshl_b32 s2, s48, 8
	v_add_u32_e32 v104, s2, v241
	v_ashrrev_i32_e32 v105, 31, v104
	v_lshl_add_u64 v[88:89], v[104:105], 2, s[70:71]
	global_load_dword v102, v[88:89], off
	s_movk_i32 s2, 0x7cf
	v_and_or_b32 v2, v104, s2, 16
	v_cmp_gt_i32_e32 vcc, s20, v104
	v_mov_b32_e32 v114, 0
	v_mov_b32_e32 v68, 1.0
	v_cndmask_b32_e32 v2, v181, v2, vcc
	v_lshlrev_b32_e32 v2, 6, v2
	v_lshl_add_u64 v[72:73], s[84:85], 0, v[2:3]
	v_lshlrev_b32_e32 v100, 2, v170
	v_mov_b32_e32 v80, 1.0
	v_mov_b32_e32 v126, 0
	v_mov_b32_e32 v82, 1.0
	v_mov_b32_e32 v124, 0
	s_and_saveexec_b64 s[2:3], s[38:39]
	s_cbranch_execz .LBB0_193
	v_mov_b32_e32 v101, v3
	v_lshl_add_u64 v[70:71], v[72:73], 0, v[100:101]
	global_load_dwordx4 v[80:83], v[70:71], off
.LBB0_193:
	s_or_b64 exec, exec, s[2:3]
	v_mov_b32_e32 v70, 1.0
	v_mov_b32_e32 v128, 0
	s_and_saveexec_b64 s[2:3], s[38:39]
	s_cbranch_execz .LBB0_195
	v_mov_b32_e32 v101, v3
	v_lshl_add_u64 v[68:69], v[72:73], 0, v[100:101]
	global_load_dwordx4 v[68:71], v[68:69], off offset:16
.LBB0_195:
	s_or_b64 exec, exec, s[2:3]
	global_load_dword v110, v[88:89], off offset:64
	s_movk_i32 s2, 0x7df
	v_or_b32_e32 v106, 16, v104
	v_bitop3_b32 v2, v104, s2, 16 bitop3:0xc8
	v_add_u32_e32 v2, 16, v2
	v_cmp_gt_i32_e32 vcc, s20, v106
	v_mov_b32_e32 v118, 0
	v_mov_b32_e32 v72, 1.0
	v_cndmask_b32_e32 v2, v181, v2, vcc
	v_lshlrev_b32_e32 v2, 6, v2
	v_lshl_add_u64 v[76:77], s[84:85], 0, v[2:3]
	v_mov_b32_e32 v84, 1.0
	v_mov_b32_e32 v132, 0
	v_mov_b32_e32 v86, 1.0
	v_mov_b32_e32 v130, 0
	s_and_saveexec_b64 s[2:3], s[38:39]
	s_cbranch_execz .LBB0_197
	v_mov_b32_e32 v101, v3
	v_lshl_add_u64 v[74:75], v[76:77], 0, v[100:101]
	global_load_dwordx4 v[84:87], v[74:75], off
.LBB0_197:
	s_or_b64 exec, exec, s[2:3]
	v_mov_b32_e32 v74, 1.0
	v_mov_b32_e32 v134, 0
	s_and_saveexec_b64 s[2:3], s[38:39]
	s_cbranch_execz .LBB0_199
	v_mov_b32_e32 v101, v3
	v_lshl_add_u64 v[72:73], v[76:77], 0, v[100:101]
	global_load_dwordx4 v[72:75], v[72:73], off offset:16
.LBB0_199:
	s_or_b64 exec, exec, s[2:3]
	global_load_dword v116, v[88:89], off offset:128
	v_or_b32_e32 v108, 32, v104
	s_movk_i32 s2, 0x7ef
	v_and_or_b32 v2, v108, s2, 16
	v_cmp_gt_i32_e32 vcc, s20, v108
	v_mov_b32_e32 v122, 0
	v_mov_b32_e32 v76, 1.0
	v_cndmask_b32_e32 v2, v181, v2, vcc
	v_lshlrev_b32_e32 v2, 6, v2
	v_lshl_add_u64 v[90:91], s[84:85], 0, v[2:3]
	v_mov_b32_e32 v92, 1.0
	v_mov_b32_e32 v138, 0
	v_mov_b32_e32 v94, 1.0
	v_mov_b32_e32 v136, 0
	s_and_saveexec_b64 s[2:3], s[38:39]
	s_cbranch_execz .LBB0_201
	v_mov_b32_e32 v101, v3
	v_lshl_add_u64 v[78:79], v[90:91], 0, v[100:101]
	global_load_dwordx4 v[92:95], v[78:79], off
.LBB0_201:
	s_or_b64 exec, exec, s[2:3]
	v_mov_b32_e32 v78, 1.0
	v_mov_b32_e32 v140, 0
	s_and_saveexec_b64 s[2:3], s[38:39]
	s_cbranch_execz .LBB0_203
	v_mov_b32_e32 v101, v3
	v_lshl_add_u64 v[76:77], v[90:91], 0, v[100:101]
	global_load_dwordx4 v[76:79], v[76:77], off offset:16
.LBB0_203:
	s_or_b64 exec, exec, s[2:3]
	global_load_dword v120, v[88:89], off offset:192
	s_movk_i32 s2, 0x7ff
	v_or_b32_e32 v112, 48, v104
	v_bitop3_b32 v2, v104, s2, 48 bitop3:0xc8
	v_add_u32_e32 v2, 16, v2
	v_cmp_gt_i32_e32 vcc, s20, v112
	v_mov_b32_e32 v88, 1.0
	v_mov_b32_e32 v96, 1.0
	v_cndmask_b32_e32 v2, v181, v2, vcc
	v_lshlrev_b32_e32 v2, 6, v2
	v_lshl_add_u64 v[148:149], s[84:85], 0, v[2:3]
	v_mov_b32_e32 v2, 0
	v_mov_b32_e32 v144, 0
	v_mov_b32_e32 v98, 1.0
	v_mov_b32_e32 v142, 0
	s_and_saveexec_b64 s[2:3], s[38:39]
	s_cbranch_execz .LBB0_205
	v_mov_b32_e32 v101, v3
	v_lshl_add_u64 v[90:91], v[148:149], 0, v[100:101]
	global_load_dwordx4 v[96:99], v[90:91], off
.LBB0_205:
	s_or_b64 exec, exec, s[2:3]
	v_mov_b32_e32 v90, 1.0
	v_mov_b32_e32 v146, 0
	s_and_saveexec_b64 s[2:3], s[38:39]
	s_cbranch_execz .LBB0_207
	v_mov_b32_e32 v101, v3
	v_lshl_add_u64 v[88:89], v[148:149], 0, v[100:101]
	global_load_dwordx4 v[88:91], v[88:89], off offset:16
.LBB0_207:
	s_or_b64 exec, exec, s[2:3]
	s_waitcnt vmcnt(0)
	s_and_saveexec_b64 s[2:3], s[38:39]
	v_mov_b32_e32 v126, v81
	v_mov_b32_e32 v124, v83
	v_mov_b32_e32 v114, v69
	v_mov_b32_e32 v128, v71
	v_mov_b32_e32 v132, v85
	v_mov_b32_e32 v130, v87
	v_mov_b32_e32 v118, v73
	v_mov_b32_e32 v134, v75
	v_mov_b32_e32 v138, v93
	v_mov_b32_e32 v136, v95
	v_mov_b32_e32 v122, v77
	v_mov_b32_e32 v140, v79
	v_mov_b32_e32 v144, v97
	v_mov_b32_e32 v142, v99
	v_mov_b32_e32 v2, v89
	v_mov_b32_e32 v146, v91
	s_or_b64 exec, exec, s[2:3]
	v_pk_mul_f32 v[148:149], v[66:67], v[102:103] op_sel_hi:[1,0]
	v_pk_mul_f32 v[150:151], v[64:65], v[102:103] op_sel_hi:[1,0]
	v_pk_mul_f32 v[124:125], v[148:149], v[124:125] op_sel:[1,0] op_sel_hi:[0,0]
	v_pk_mul_f32 v[126:127], v[150:151], v[126:127] op_sel:[1,0] op_sel_hi:[0,0]
	v_pk_fma_f32 v[152:153], v[150:151], v[80:81], v[126:127] op_sel_hi:[1,0,1] neg_lo:[0,0,1] neg_hi:[0,0,1]
	v_pk_fma_f32 v[80:81], v[150:151], v[80:81], v[126:127] op_sel_hi:[1,0,1]
	v_pk_fma_f32 v[126:127], v[148:149], v[82:83], v[124:125] op_sel_hi:[1,0,1] neg_lo:[0,0,1] neg_hi:[0,0,1]
	v_pk_fma_f32 v[82:83], v[148:149], v[82:83], v[124:125] op_sel_hi:[1,0,1]
	v_pk_mul_f32 v[124:125], v[62:63], v[102:103] op_sel_hi:[1,0]
	v_pk_mul_f32 v[102:103], v[60:61], v[102:103] op_sel_hi:[1,0]
	v_mov_b32_e32 v127, v83
	s_mov_b32 s4, 0x3e000000
	v_pk_mul_f32 v[114:115], v[102:103], v[114:115] op_sel:[1,0] op_sel_hi:[0,0]
	v_pk_mul_f32 v[82:83], v[126:127], s[4:5] op_sel_hi:[1,0]
	v_pk_fma_f32 v[126:127], v[102:103], v[68:69], v[114:115] op_sel_hi:[1,0,1] neg_lo:[0,0,1] neg_hi:[0,0,1]
	v_pk_fma_f32 v[68:69], v[102:103], v[68:69], v[114:115] op_sel_hi:[1,0,1]
	v_pk_mul_f32 v[102:103], v[124:125], v[128:129] op_sel:[1,0] op_sel_hi:[0,0]
	s_ashr_i32 s75, s74, 31
	v_pk_fma_f32 v[114:115], v[124:125], v[70:71], v[102:103] op_sel_hi:[1,0,1] neg_lo:[0,0,1] neg_hi:[0,0,1]
	v_pk_fma_f32 v[70:71], v[124:125], v[70:71], v[102:103] op_sel_hi:[1,0,1]
	v_mov_b32_e32 v127, v69
	v_lshlrev_b64 v[68:69], 10, v[104:105]
	v_lshl_add_u64 v[102:103], s[74:75], 0, v[178:179]
	v_mov_b32_e32 v153, v81
	v_lshl_add_u64 v[68:69], s[94:95], 0, v[68:69]
	v_lshlrev_b64 v[102:103], 1, v[102:103]
	v_pk_mul_f32 v[80:81], v[152:153], s[4:5] op_sel_hi:[1,0]
	v_mov_b32_e32 v115, v71
	v_lshl_add_u64 v[124:125], v[68:69], 0, v[102:103]
	s_mov_b32 s2, 0x847e000
	v_pk_mul_f32 v[114:115], v[114:115], s[4:5] op_sel_hi:[1,0]
	v_pk_mul_f32 v[70:71], v[126:127], s[4:5] op_sel_hi:[1,0]
	v_cvt_pk_bf16_f32 v68, v80, v81
	v_add_co_u32_e32 v80, vcc, s2, v124
	v_cvt_pk_bf16_f32 v69, v82, v83
	v_cvt_pk_bf16_f32 v70, v70, v71
	v_cvt_pk_bf16_f32 v71, v114, v115
	v_addc_co_u32_e32 v81, vcc, 0, v125, vcc
	global_store_dwordx4 v[80:81], v[68:71], off offset:2304
	v_ashrrev_i32_e32 v107, 31, v106
	v_ashrrev_i32_e32 v109, 31, v108
	v_pk_mul_f32 v[70:71], v[56:57], v[110:111] op_sel_hi:[1,0]
	v_pk_mul_f32 v[68:69], v[58:59], v[110:111] op_sel_hi:[1,0]
	v_pk_mul_f32 v[80:81], v[70:71], v[132:133] op_sel:[1,0] op_sel_hi:[0,0]
	v_pk_fma_f32 v[82:83], v[70:71], v[84:85], v[80:81] op_sel_hi:[1,0,1] neg_lo:[0,0,1] neg_hi:[0,0,1]
	v_pk_fma_f32 v[70:71], v[70:71], v[84:85], v[80:81] op_sel_hi:[1,0,1]
	v_pk_mul_f32 v[80:81], v[68:69], v[130:131] op_sel:[1,0] op_sel_hi:[0,0]
	v_pk_fma_f32 v[84:85], v[68:69], v[86:87], v[80:81] op_sel_hi:[1,0,1] neg_lo:[0,0,1] neg_hi:[0,0,1]
	v_pk_fma_f32 v[68:69], v[68:69], v[86:87], v[80:81] op_sel_hi:[1,0,1]
	v_mov_b32_e32 v83, v71
	v_mov_b32_e32 v85, v69
	v_pk_mul_f32 v[68:69], v[82:83], s[4:5] op_sel_hi:[1,0]
	v_pk_mul_f32 v[82:83], v[52:53], v[110:111] op_sel_hi:[1,0]
	v_pk_mul_f32 v[80:81], v[84:85], s[4:5] op_sel_hi:[1,0]
	v_pk_mul_f32 v[84:85], v[82:83], v[118:119] op_sel:[1,0] op_sel_hi:[0,0]
	v_pk_mul_f32 v[70:71], v[54:55], v[110:111] op_sel_hi:[1,0]
	v_pk_fma_f32 v[86:87], v[82:83], v[72:73], v[84:85] op_sel_hi:[1,0,1] neg_lo:[0,0,1] neg_hi:[0,0,1]
	v_pk_fma_f32 v[72:73], v[82:83], v[72:73], v[84:85] op_sel_hi:[1,0,1]
	v_pk_mul_f32 v[82:83], v[70:71], v[134:135] op_sel:[1,0] op_sel_hi:[0,0]
	v_mov_b32_e32 v87, v73
	v_lshlrev_b64 v[72:73], 10, v[106:107]
	v_pk_fma_f32 v[84:85], v[70:71], v[74:75], v[82:83] op_sel_hi:[1,0,1] neg_lo:[0,0,1] neg_hi:[0,0,1]
	v_pk_fma_f32 v[70:71], v[70:71], v[74:75], v[82:83] op_sel_hi:[1,0,1]
	v_lshl_add_u64 v[72:73], s[94:95], 0, v[72:73]
	v_mov_b32_e32 v85, v71
	v_lshl_add_u64 v[72:73], v[72:73], 0, v[102:103]
	v_pk_mul_f32 v[74:75], v[84:85], s[4:5] op_sel_hi:[1,0]
	v_pk_mul_f32 v[70:71], v[86:87], s[4:5] op_sel_hi:[1,0]
	v_add_co_u32_e32 v72, vcc, s2, v72
	v_cvt_pk_bf16_f32 v68, v68, v69
	v_cvt_pk_bf16_f32 v69, v80, v81
	v_cvt_pk_bf16_f32 v70, v70, v71
	v_cvt_pk_bf16_f32 v71, v74, v75
	v_addc_co_u32_e32 v73, vcc, 0, v73, vcc
	global_store_dwordx4 v[72:73], v[68:71], off offset:2304
	v_ashrrev_i32_e32 v113, 31, v112
	s_cmp_eq_u32 s48, 64
	v_pk_mul_f32 v[70:71], v[48:49], v[116:117] op_sel_hi:[1,0]
	v_pk_mul_f32 v[68:69], v[50:51], v[116:117] op_sel_hi:[1,0]
	v_pk_mul_f32 v[72:73], v[70:71], v[138:139] op_sel:[1,0] op_sel_hi:[0,0]
	v_pk_fma_f32 v[74:75], v[70:71], v[92:93], v[72:73] op_sel_hi:[1,0,1] neg_lo:[0,0,1] neg_hi:[0,0,1]
	v_pk_fma_f32 v[70:71], v[70:71], v[92:93], v[72:73] op_sel_hi:[1,0,1]
	v_pk_mul_f32 v[72:73], v[68:69], v[136:137] op_sel:[1,0] op_sel_hi:[0,0]
	v_pk_fma_f32 v[80:81], v[68:69], v[94:95], v[72:73] op_sel_hi:[1,0,1] neg_lo:[0,0,1] neg_hi:[0,0,1]
	v_pk_fma_f32 v[68:69], v[68:69], v[94:95], v[72:73] op_sel_hi:[1,0,1]
	v_mov_b32_e32 v75, v71
	v_mov_b32_e32 v81, v69
	v_pk_mul_f32 v[68:69], v[74:75], s[4:5] op_sel_hi:[1,0]
	v_pk_mul_f32 v[74:75], v[44:45], v[116:117] op_sel_hi:[1,0]
	v_pk_mul_f32 v[72:73], v[80:81], s[4:5] op_sel_hi:[1,0]
	v_pk_mul_f32 v[80:81], v[74:75], v[122:123] op_sel:[1,0] op_sel_hi:[0,0]
	v_pk_mul_f32 v[70:71], v[46:47], v[116:117] op_sel_hi:[1,0]
	v_pk_fma_f32 v[82:83], v[74:75], v[76:77], v[80:81] op_sel_hi:[1,0,1] neg_lo:[0,0,1] neg_hi:[0,0,1]
	v_pk_fma_f32 v[74:75], v[74:75], v[76:77], v[80:81] op_sel_hi:[1,0,1]
	v_pk_mul_f32 v[76:77], v[70:71], v[140:141] op_sel:[1,0] op_sel_hi:[0,0]
	v_mov_b32_e32 v83, v75
	v_lshlrev_b64 v[74:75], 10, v[108:109]
	v_pk_fma_f32 v[80:81], v[70:71], v[78:79], v[76:77] op_sel_hi:[1,0,1] neg_lo:[0,0,1] neg_hi:[0,0,1]
	v_pk_fma_f32 v[70:71], v[70:71], v[78:79], v[76:77] op_sel_hi:[1,0,1]
	v_lshl_add_u64 v[74:75], s[94:95], 0, v[74:75]
	v_mov_b32_e32 v81, v71
	v_lshl_add_u64 v[74:75], v[74:75], 0, v[102:103]
	v_pk_mul_f32 v[76:77], v[80:81], s[4:5] op_sel_hi:[1,0]
	v_pk_mul_f32 v[70:71], v[82:83], s[4:5] op_sel_hi:[1,0]
	v_cvt_pk_bf16_f32 v68, v68, v69
	v_cvt_pk_bf16_f32 v69, v72, v73
	v_add_co_u32_e32 v72, vcc, s2, v74
	v_cvt_pk_bf16_f32 v70, v70, v71
	v_cvt_pk_bf16_f32 v71, v76, v77
	v_addc_co_u32_e32 v73, vcc, 0, v75, vcc
	global_store_dwordx4 v[72:73], v[68:71], off offset:2304
	s_nop 1
	v_pk_mul_f32 v[70:71], v[40:41], v[120:121] op_sel_hi:[1,0]
	v_pk_mul_f32 v[68:69], v[42:43], v[120:121] op_sel_hi:[1,0]
	v_pk_mul_f32 v[72:73], v[70:71], v[144:145] op_sel:[1,0] op_sel_hi:[0,0]
	v_pk_fma_f32 v[74:75], v[70:71], v[96:97], v[72:73] op_sel_hi:[1,0,1] neg_lo:[0,0,1] neg_hi:[0,0,1]
	v_pk_fma_f32 v[70:71], v[70:71], v[96:97], v[72:73] op_sel_hi:[1,0,1]
	v_pk_mul_f32 v[72:73], v[68:69], v[142:143] op_sel:[1,0] op_sel_hi:[0,0]
	v_pk_fma_f32 v[76:77], v[68:69], v[98:99], v[72:73] op_sel_hi:[1,0,1] neg_lo:[0,0,1] neg_hi:[0,0,1]
	v_pk_fma_f32 v[68:69], v[68:69], v[98:99], v[72:73] op_sel_hi:[1,0,1]
	v_mov_b32_e32 v75, v71
	v_mov_b32_e32 v77, v69
	v_pk_mul_f32 v[68:69], v[74:75], s[4:5] op_sel_hi:[1,0]
	v_pk_mul_f32 v[74:75], v[36:37], v[120:121] op_sel_hi:[1,0]
	v_pk_mul_f32 v[72:73], v[76:77], s[4:5] op_sel_hi:[1,0]
	v_pk_mul_f32 v[76:77], v[74:75], v[2:3] op_sel:[1,0] op_sel_hi:[0,0]
	v_pk_mul_f32 v[70:71], v[38:39], v[120:121] op_sel_hi:[1,0]
	v_pk_fma_f32 v[78:79], v[74:75], v[88:89], v[76:77] op_sel_hi:[1,0,1] neg_lo:[0,0,1] neg_hi:[0,0,1]
	v_pk_fma_f32 v[74:75], v[74:75], v[88:89], v[76:77] op_sel_hi:[1,0,1]
	v_pk_mul_f32 v[76:77], v[70:71], v[146:147] op_sel:[1,0] op_sel_hi:[0,0]
	v_mov_b32_e32 v79, v75
	v_lshlrev_b64 v[74:75], 10, v[112:113]
	v_pk_fma_f32 v[80:81], v[70:71], v[90:91], v[76:77] op_sel_hi:[1,0,1] neg_lo:[0,0,1] neg_hi:[0,0,1]
	v_pk_fma_f32 v[70:71], v[70:71], v[90:91], v[76:77] op_sel_hi:[1,0,1]
	v_lshl_add_u64 v[74:75], s[94:95], 0, v[74:75]
	v_mov_b32_e32 v81, v71
	v_lshl_add_u64 v[74:75], v[74:75], 0, v[102:103]
	v_pk_mul_f32 v[76:77], v[80:81], s[4:5] op_sel_hi:[1,0]
	v_pk_mul_f32 v[70:71], v[78:79], s[4:5] op_sel_hi:[1,0]
	v_cvt_pk_bf16_f32 v68, v68, v69
	v_cvt_pk_bf16_f32 v69, v72, v73
	v_add_co_u32_e32 v72, vcc, 0x847e000, v74
	v_cvt_pk_bf16_f32 v70, v70, v71
	v_cvt_pk_bf16_f32 v71, v76, v77
	v_addc_co_u32_e32 v73, vcc, 0, v75, vcc
	global_store_dwordx4 v[72:73], v[68:71], off offset:2304
	s_cbranch_scc1 .LBB0_225
	v_add_u32_e32 v104, 0x80, v104
	v_ashrrev_i32_e32 v105, 31, v104
	v_lshl_add_u64 v[88:89], v[104:105], 2, s[70:71]
	global_load_dword v108, v[88:89], off
	s_movk_i32 s2, 0x7cf
	v_and_or_b32 v2, v104, s2, 16
	v_cmp_gt_i32_e32 vcc, s20, v104
	v_mov_b32_e32 v114, 0
	v_mov_b32_e32 v68, 1.0
	v_cndmask_b32_e32 v2, v181, v2, vcc
	v_lshlrev_b32_e32 v2, 6, v2
	v_lshl_add_u64 v[72:73], s[84:85], 0, v[2:3]
	v_mov_b32_e32 v76, 1.0
	v_mov_b32_e32 v126, 0
	v_mov_b32_e32 v78, 1.0
	v_mov_b32_e32 v124, 0
	s_and_saveexec_b64 s[2:3], s[38:39]
	s_cbranch_execz .LBB0_210
	v_mov_b32_e32 v101, v3
	v_lshl_add_u64 v[70:71], v[72:73], 0, v[100:101]
	global_load_dwordx4 v[76:79], v[70:71], off
.LBB0_210:
	s_or_b64 exec, exec, s[2:3]
	v_mov_b32_e32 v70, 1.0
	v_mov_b32_e32 v130, 0
	s_and_saveexec_b64 s[2:3], s[38:39]
	s_cbranch_execz .LBB0_212
	v_mov_b32_e32 v101, v3
	v_lshl_add_u64 v[68:69], v[72:73], 0, v[100:101]
	global_load_dwordx4 v[68:71], v[68:69], off offset:16
.LBB0_212:
	s_or_b64 exec, exec, s[2:3]
	global_load_dword v112, v[88:89], off offset:64
	s_movk_i32 s2, 0x7df
	v_or_b32_e32 v106, 16, v104
	v_bitop3_b32 v2, v104, s2, 16 bitop3:0xc8
	v_add_u32_e32 v2, 16, v2
	v_cmp_gt_i32_e32 vcc, s20, v106
	v_mov_b32_e32 v120, 0
	v_mov_b32_e32 v72, 1.0
	v_cndmask_b32_e32 v2, v181, v2, vcc
	v_lshlrev_b32_e32 v2, 6, v2
	v_lshl_add_u64 v[80:81], s[84:85], 0, v[2:3]
	v_mov_b32_e32 v84, 1.0
	v_mov_b32_e32 v134, 0
	v_mov_b32_e32 v86, 1.0
	v_mov_b32_e32 v132, 0
	s_and_saveexec_b64 s[2:3], s[38:39]
	s_cbranch_execz .LBB0_214
	v_mov_b32_e32 v101, v3
	v_lshl_add_u64 v[74:75], v[80:81], 0, v[100:101]
	global_load_dwordx4 v[84:87], v[74:75], off
.LBB0_214:
	s_or_b64 exec, exec, s[2:3]
	v_mov_b32_e32 v74, 1.0
	v_mov_b32_e32 v136, 0
	s_and_saveexec_b64 s[2:3], s[38:39]
	s_cbranch_execz .LBB0_216
	v_mov_b32_e32 v101, v3
	v_lshl_add_u64 v[72:73], v[80:81], 0, v[100:101]
	global_load_dwordx4 v[72:75], v[72:73], off offset:16
.LBB0_216:
	s_or_b64 exec, exec, s[2:3]
	global_load_dword v118, v[88:89], off offset:128
	v_or_b32_e32 v110, 32, v104
	s_movk_i32 s2, 0x7ef
	v_and_or_b32 v2, v110, s2, 16
	v_cmp_gt_i32_e32 vcc, s20, v110
	v_mov_b32_e32 v128, 0
	v_mov_b32_e32 v80, 1.0
	v_cndmask_b32_e32 v2, v181, v2, vcc
	v_lshlrev_b32_e32 v2, 6, v2
	v_lshl_add_u64 v[90:91], s[84:85], 0, v[2:3]
	v_mov_b32_e32 v92, 1.0
	v_mov_b32_e32 v140, 0
	v_mov_b32_e32 v94, 1.0
	v_mov_b32_e32 v138, 0
	s_and_saveexec_b64 s[2:3], s[38:39]
	s_cbranch_execz .LBB0_218
	v_mov_b32_e32 v101, v3
	v_lshl_add_u64 v[82:83], v[90:91], 0, v[100:101]
	global_load_dwordx4 v[92:95], v[82:83], off
.LBB0_218:
	s_or_b64 exec, exec, s[2:3]
	v_mov_b32_e32 v82, 1.0
	v_mov_b32_e32 v142, 0
	s_and_saveexec_b64 s[2:3], s[38:39]
	s_cbranch_execz .LBB0_220
	v_mov_b32_e32 v101, v3
	v_lshl_add_u64 v[80:81], v[90:91], 0, v[100:101]
	global_load_dwordx4 v[80:83], v[80:81], off offset:16
.LBB0_220:
	s_or_b64 exec, exec, s[2:3]
	global_load_dword v122, v[88:89], off offset:192
	s_movk_i32 s2, 0x7ff
	v_or_b32_e32 v116, 48, v104
	v_bitop3_b32 v2, v104, s2, 48 bitop3:0xc8
	v_add_u32_e32 v2, 16, v2
	v_cmp_gt_i32_e32 vcc, s20, v116
	v_mov_b32_e32 v88, 1.0
	v_mov_b32_e32 v96, 1.0
	v_cndmask_b32_e32 v2, v181, v2, vcc
	v_lshlrev_b32_e32 v2, 6, v2
	v_lshl_add_u64 v[150:151], s[84:85], 0, v[2:3]
	v_mov_b32_e32 v2, 0
	v_mov_b32_e32 v146, 0
	v_mov_b32_e32 v98, 1.0
	v_mov_b32_e32 v144, 0
	s_and_saveexec_b64 s[2:3], s[38:39]
	s_cbranch_execz .LBB0_222
	v_mov_b32_e32 v101, v3
	v_lshl_add_u64 v[90:91], v[150:151], 0, v[100:101]
	global_load_dwordx4 v[96:99], v[90:91], off
.LBB0_222:
	s_or_b64 exec, exec, s[2:3]
	v_mov_b32_e32 v90, 1.0
	v_mov_b32_e32 v148, 0
	s_and_saveexec_b64 s[2:3], s[38:39]
	s_cbranch_execz .LBB0_224
	v_mov_b32_e32 v101, v3
	v_lshl_add_u64 v[88:89], v[150:151], 0, v[100:101]
	global_load_dwordx4 v[88:91], v[88:89], off offset:16
.LBB0_224:
	s_or_b64 exec, exec, s[2:3]
	s_waitcnt vmcnt(0)
	s_and_saveexec_b64 s[2:3], s[38:39]
	v_mov_b32_e32 v126, v77
	v_mov_b32_e32 v124, v79
	v_mov_b32_e32 v114, v69
	v_mov_b32_e32 v130, v71
	v_mov_b32_e32 v134, v85
	v_mov_b32_e32 v132, v87
	v_mov_b32_e32 v120, v73
	v_mov_b32_e32 v136, v75
	v_mov_b32_e32 v140, v93
	v_mov_b32_e32 v138, v95
	v_mov_b32_e32 v128, v81
	v_mov_b32_e32 v142, v83
	v_mov_b32_e32 v146, v97
	v_mov_b32_e32 v144, v99
	v_mov_b32_e32 v2, v89
	v_mov_b32_e32 v148, v91
	s_or_b64 exec, exec, s[2:3]
	v_pk_mul_f32 v[100:101], v[34:35], v[108:109] op_sel_hi:[1,0]
	v_pk_mul_f32 v[150:151], v[32:33], v[108:109] op_sel_hi:[1,0]
	v_pk_mul_f32 v[124:125], v[100:101], v[124:125] op_sel:[1,0] op_sel_hi:[0,0]
	v_pk_mul_f32 v[126:127], v[150:151], v[126:127] op_sel:[1,0] op_sel_hi:[0,0]
	v_pk_fma_f32 v[152:153], v[150:151], v[76:77], v[126:127] op_sel_hi:[1,0,1] neg_lo:[0,0,1] neg_hi:[0,0,1]
	v_pk_fma_f32 v[76:77], v[150:151], v[76:77], v[126:127] op_sel_hi:[1,0,1]
	v_pk_fma_f32 v[126:127], v[100:101], v[78:79], v[124:125] op_sel_hi:[1,0,1] neg_lo:[0,0,1] neg_hi:[0,0,1]
	v_pk_fma_f32 v[78:79], v[100:101], v[78:79], v[124:125] op_sel_hi:[1,0,1]
	v_pk_mul_f32 v[100:101], v[30:31], v[108:109] op_sel_hi:[1,0]
	v_pk_mul_f32 v[108:109], v[28:29], v[108:109] op_sel_hi:[1,0]
	v_mov_b32_e32 v153, v77
	v_pk_mul_f32 v[114:115], v[108:109], v[114:115] op_sel:[1,0] op_sel_hi:[0,0]
	v_pk_fma_f32 v[124:125], v[108:109], v[68:69], v[114:115] op_sel_hi:[1,0,1] neg_lo:[0,0,1] neg_hi:[0,0,1]
	v_pk_fma_f32 v[68:69], v[108:109], v[68:69], v[114:115] op_sel_hi:[1,0,1]
	v_pk_mul_f32 v[108:109], v[100:101], v[130:131] op_sel:[1,0] op_sel_hi:[0,0]
	v_mov_b32_e32 v125, v69
	v_lshlrev_b64 v[68:69], 10, v[104:105]
	v_pk_fma_f32 v[114:115], v[100:101], v[70:71], v[108:109] op_sel_hi:[1,0,1] neg_lo:[0,0,1] neg_hi:[0,0,1]
	v_pk_fma_f32 v[70:71], v[100:101], v[70:71], v[108:109] op_sel_hi:[1,0,1]
	v_lshl_add_u64 v[68:69], s[94:95], 0, v[68:69]
	v_mov_b32_e32 v127, v79
	v_pk_mul_f32 v[76:77], v[152:153], s[4:5] op_sel_hi:[1,0]
	v_mov_b32_e32 v115, v71
	v_lshl_add_u64 v[104:105], v[68:69], 0, v[102:103]
	s_mov_b32 s2, 0x847e000
	v_pk_mul_f32 v[78:79], v[126:127], s[4:5] op_sel_hi:[1,0]
	v_pk_mul_f32 v[100:101], v[114:115], s[4:5] op_sel_hi:[1,0]
	v_pk_mul_f32 v[70:71], v[124:125], s[4:5] op_sel_hi:[1,0]
	v_cvt_pk_bf16_f32 v68, v76, v77
	v_add_co_u32_e32 v76, vcc, s2, v104
	v_cvt_pk_bf16_f32 v69, v78, v79
	v_cvt_pk_bf16_f32 v70, v70, v71
	v_cvt_pk_bf16_f32 v71, v100, v101
	v_addc_co_u32_e32 v77, vcc, 0, v105, vcc
	global_store_dwordx4 v[76:77], v[68:71], off offset:2304
	v_ashrrev_i32_e32 v107, 31, v106
	v_ashrrev_i32_e32 v111, 31, v110
	v_pk_mul_f32 v[70:71], v[24:25], v[112:113] op_sel_hi:[1,0]
	v_pk_mul_f32 v[68:69], v[26:27], v[112:113] op_sel_hi:[1,0]
	v_pk_mul_f32 v[76:77], v[70:71], v[134:135] op_sel:[1,0] op_sel_hi:[0,0]
	v_pk_fma_f32 v[78:79], v[70:71], v[84:85], v[76:77] op_sel_hi:[1,0,1] neg_lo:[0,0,1] neg_hi:[0,0,1]
	v_pk_fma_f32 v[70:71], v[70:71], v[84:85], v[76:77] op_sel_hi:[1,0,1]
	v_pk_mul_f32 v[76:77], v[68:69], v[132:133] op_sel:[1,0] op_sel_hi:[0,0]
	v_pk_fma_f32 v[84:85], v[68:69], v[86:87], v[76:77] op_sel_hi:[1,0,1] neg_lo:[0,0,1] neg_hi:[0,0,1]
	v_pk_fma_f32 v[68:69], v[68:69], v[86:87], v[76:77] op_sel_hi:[1,0,1]
	v_mov_b32_e32 v79, v71
	v_mov_b32_e32 v85, v69
	v_pk_mul_f32 v[68:69], v[78:79], s[4:5] op_sel_hi:[1,0]
	v_pk_mul_f32 v[78:79], v[20:21], v[112:113] op_sel_hi:[1,0]
	v_pk_mul_f32 v[76:77], v[84:85], s[4:5] op_sel_hi:[1,0]
	v_pk_mul_f32 v[84:85], v[78:79], v[120:121] op_sel:[1,0] op_sel_hi:[0,0]
	v_pk_mul_f32 v[70:71], v[22:23], v[112:113] op_sel_hi:[1,0]
	v_pk_fma_f32 v[86:87], v[78:79], v[72:73], v[84:85] op_sel_hi:[1,0,1] neg_lo:[0,0,1] neg_hi:[0,0,1]
	v_pk_fma_f32 v[72:73], v[78:79], v[72:73], v[84:85] op_sel_hi:[1,0,1]
	v_pk_mul_f32 v[78:79], v[70:71], v[136:137] op_sel:[1,0] op_sel_hi:[0,0]
	v_mov_b32_e32 v87, v73
	v_lshlrev_b64 v[72:73], 10, v[106:107]
	v_pk_fma_f32 v[84:85], v[70:71], v[74:75], v[78:79] op_sel_hi:[1,0,1] neg_lo:[0,0,1] neg_hi:[0,0,1]
	v_pk_fma_f32 v[70:71], v[70:71], v[74:75], v[78:79] op_sel_hi:[1,0,1]
	v_lshl_add_u64 v[72:73], s[94:95], 0, v[72:73]
	v_mov_b32_e32 v85, v71
	v_lshl_add_u64 v[72:73], v[72:73], 0, v[102:103]
	v_pk_mul_f32 v[74:75], v[84:85], s[4:5] op_sel_hi:[1,0]
	v_pk_mul_f32 v[70:71], v[86:87], s[4:5] op_sel_hi:[1,0]
	v_add_co_u32_e32 v72, vcc, s2, v72
	v_cvt_pk_bf16_f32 v68, v68, v69
	v_cvt_pk_bf16_f32 v69, v76, v77
	v_cvt_pk_bf16_f32 v70, v70, v71
	v_cvt_pk_bf16_f32 v71, v74, v75
	v_addc_co_u32_e32 v73, vcc, 0, v73, vcc
	global_store_dwordx4 v[72:73], v[68:71], off offset:2304
	v_ashrrev_i32_e32 v117, 31, v116
	s_nop 0
	v_pk_mul_f32 v[70:71], v[16:17], v[118:119] op_sel_hi:[1,0]
	v_pk_mul_f32 v[68:69], v[18:19], v[118:119] op_sel_hi:[1,0]
	v_pk_mul_f32 v[72:73], v[70:71], v[140:141] op_sel:[1,0] op_sel_hi:[0,0]
	v_pk_fma_f32 v[74:75], v[70:71], v[92:93], v[72:73] op_sel_hi:[1,0,1] neg_lo:[0,0,1] neg_hi:[0,0,1]
	v_pk_fma_f32 v[70:71], v[70:71], v[92:93], v[72:73] op_sel_hi:[1,0,1]
	v_pk_mul_f32 v[72:73], v[68:69], v[138:139] op_sel:[1,0] op_sel_hi:[0,0]
	v_pk_fma_f32 v[76:77], v[68:69], v[94:95], v[72:73] op_sel_hi:[1,0,1] neg_lo:[0,0,1] neg_hi:[0,0,1]
	v_pk_fma_f32 v[68:69], v[68:69], v[94:95], v[72:73] op_sel_hi:[1,0,1]
	v_mov_b32_e32 v75, v71
	v_mov_b32_e32 v77, v69
	v_pk_mul_f32 v[68:69], v[74:75], s[4:5] op_sel_hi:[1,0]
	v_pk_mul_f32 v[74:75], v[12:13], v[118:119] op_sel_hi:[1,0]
	v_pk_mul_f32 v[72:73], v[76:77], s[4:5] op_sel_hi:[1,0]
	v_pk_mul_f32 v[76:77], v[74:75], v[128:129] op_sel:[1,0] op_sel_hi:[0,0]
	v_pk_mul_f32 v[70:71], v[14:15], v[118:119] op_sel_hi:[1,0]
	v_pk_fma_f32 v[78:79], v[74:75], v[80:81], v[76:77] op_sel_hi:[1,0,1] neg_lo:[0,0,1] neg_hi:[0,0,1]
	v_pk_fma_f32 v[74:75], v[74:75], v[80:81], v[76:77] op_sel_hi:[1,0,1]
	v_pk_mul_f32 v[76:77], v[70:71], v[142:143] op_sel:[1,0] op_sel_hi:[0,0]
	v_mov_b32_e32 v79, v75
	v_lshlrev_b64 v[74:75], 10, v[110:111]
	v_pk_fma_f32 v[80:81], v[70:71], v[82:83], v[76:77] op_sel_hi:[1,0,1] neg_lo:[0,0,1] neg_hi:[0,0,1]
	v_pk_fma_f32 v[70:71], v[70:71], v[82:83], v[76:77] op_sel_hi:[1,0,1]
	v_lshl_add_u64 v[74:75], s[94:95], 0, v[74:75]
	v_mov_b32_e32 v81, v71
	v_lshl_add_u64 v[74:75], v[74:75], 0, v[102:103]
	v_pk_mul_f32 v[76:77], v[80:81], s[4:5] op_sel_hi:[1,0]
	v_pk_mul_f32 v[70:71], v[78:79], s[4:5] op_sel_hi:[1,0]
	v_cvt_pk_bf16_f32 v68, v68, v69
	v_cvt_pk_bf16_f32 v69, v72, v73
	v_add_co_u32_e32 v72, vcc, s2, v74
	v_cvt_pk_bf16_f32 v70, v70, v71
	v_cvt_pk_bf16_f32 v71, v76, v77
	v_addc_co_u32_e32 v73, vcc, 0, v75, vcc
	global_store_dwordx4 v[72:73], v[68:71], off offset:2304
	s_nop 1
	v_pk_mul_f32 v[70:71], v[8:9], v[122:123] op_sel_hi:[1,0]
	v_pk_mul_f32 v[68:69], v[10:11], v[122:123] op_sel_hi:[1,0]
	v_pk_mul_f32 v[72:73], v[70:71], v[146:147] op_sel:[1,0] op_sel_hi:[0,0]
	v_pk_fma_f32 v[74:75], v[70:71], v[96:97], v[72:73] op_sel_hi:[1,0,1] neg_lo:[0,0,1] neg_hi:[0,0,1]
	v_pk_fma_f32 v[70:71], v[70:71], v[96:97], v[72:73] op_sel_hi:[1,0,1]
	v_pk_mul_f32 v[72:73], v[68:69], v[144:145] op_sel:[1,0] op_sel_hi:[0,0]
	v_pk_fma_f32 v[76:77], v[68:69], v[98:99], v[72:73] op_sel_hi:[1,0,1] neg_lo:[0,0,1] neg_hi:[0,0,1]
	v_pk_fma_f32 v[68:69], v[68:69], v[98:99], v[72:73] op_sel_hi:[1,0,1]
	v_mov_b32_e32 v75, v71
	v_mov_b32_e32 v77, v69
	v_pk_mul_f32 v[68:69], v[74:75], s[4:5] op_sel_hi:[1,0]
	v_pk_mul_f32 v[74:75], v[4:5], v[122:123] op_sel_hi:[1,0]
	v_pk_mul_f32 v[72:73], v[76:77], s[4:5] op_sel_hi:[1,0]
	v_pk_mul_f32 v[76:77], v[74:75], v[2:3] op_sel:[1,0] op_sel_hi:[0,0]
	v_pk_mul_f32 v[70:71], v[6:7], v[122:123] op_sel_hi:[1,0]
	v_pk_fma_f32 v[78:79], v[74:75], v[88:89], v[76:77] op_sel_hi:[1,0,1] neg_lo:[0,0,1] neg_hi:[0,0,1]
	v_pk_fma_f32 v[74:75], v[74:75], v[88:89], v[76:77] op_sel_hi:[1,0,1]
	v_pk_mul_f32 v[76:77], v[70:71], v[148:149] op_sel:[1,0] op_sel_hi:[0,0]
	v_mov_b32_e32 v79, v75
	v_lshlrev_b64 v[74:75], 10, v[116:117]
	v_pk_fma_f32 v[80:81], v[70:71], v[90:91], v[76:77] op_sel_hi:[1,0,1] neg_lo:[0,0,1] neg_hi:[0,0,1]
	v_pk_fma_f32 v[70:71], v[70:71], v[90:91], v[76:77] op_sel_hi:[1,0,1]
	v_lshl_add_u64 v[74:75], s[94:95], 0, v[74:75]
	v_mov_b32_e32 v81, v71
	v_lshl_add_u64 v[74:75], v[74:75], 0, v[102:103]
	v_pk_mul_f32 v[76:77], v[80:81], s[4:5] op_sel_hi:[1,0]
	v_pk_mul_f32 v[70:71], v[78:79], s[4:5] op_sel_hi:[1,0]
	v_cvt_pk_bf16_f32 v68, v68, v69
	v_cvt_pk_bf16_f32 v69, v72, v73
	v_add_co_u32_e32 v72, vcc, 0x847e000, v74
	v_cvt_pk_bf16_f32 v70, v70, v71
	v_cvt_pk_bf16_f32 v71, v76, v77
	v_addc_co_u32_e32 v73, vcc, 0, v75, vcc
	global_store_dwordx4 v[72:73], v[68:71], off offset:2304
